# v41 plus: in follow-on units the leading half defers the wait that retires K-tile 2's first stages to the closing barrier of that segment (one more MFMA block for the epilogue stores to drain)
# speedup vs baseline: 1.0012x; 1.0012x over previous
; #define PG8_STAGE(bufoff, gbase, voff) do { _Pragma("unroll") for (int _i = 0; _i < 2; ++_i) \
;         __builtin_amdgcn_global_load_lds((const unsigned*)((const char*)(gbase) + (voff)[_i]), (PG8_LAS unsigned*)(lds + (bufoff) + ldsw + _i * 8192), 16, 0, 0); } while (0)
; #define PG8_LDA(dst, b, h) do { _Pragma("unroll") for (int m = 0; m < 4; ++m) _Pragma("unroll") for (int k = 0; k < 2; ++k) dst[m][k] = *(const PG8_LAS bf16x8*)(lds + PG8_SA(b, h) + aoff + m * 2048 + k * 1024); } while (0)
; #define PG8_LDB(dst, b, h) do { _Pragma("unroll") for (int n = 0; n < 2; ++n) _Pragma("unroll") for (int k = 0; k < 2; ++k) dst[n][k] = *(const PG8_LAS bf16x8*)(lds + PG8_SB(b, h) + boff + n * 2048 + k * 1024); } while (0)
; #define PG8_MMA(ai, bj, At, Bt) do { __builtin_amdgcn_s_setprio(1); _Pragma("unroll") for (int m = 0; m < 4; ++m) _Pragma("unroll") for (int n = 0; n < 2; ++n) _Pragma("unroll") for (int k = 0; k < 2; ++k) \
;         acc[ai][bj][m][n] = __builtin_amdgcn_mfma_f32_16x16x32_bf16(Bt[n][k], At[m][k], acc[ai][bj][m][n], 0, 0, 0); __builtin_amdgcn_s_setprio(0); } while (0)
; #define PG8_WAIT_V(n) asm volatile("s_waitcnt vmcnt(" #n ")" ::: "memory")
; #define PG8_WAIT_L(n) asm volatile("s_waitcnt lgkmcnt(" #n ")" ::: "memory")
; #define PG8_BAR __builtin_amdgcn_s_barrier()
; #define PG8_SCHED __builtin_amdgcn_sched_barrier(0)
; template <class Epi, class Sched, bool ALIGN_EPI = false, bool SP2 = false>
; __device__ __forceinline__ void gemm_phase(PG8_LAS unsigned char* lds, const Gemm g, const Sched& S, const Epi& E) {
;     ...
;             PG8_LDB(B0, 0, 0); PG8_LDB(B1, 0, 1); PG8_SCHED; PG8_LDA(At, 0, 0); PG8_STAGE(PG8_SA(1, 1), a1 + hstep, voffA);
;             PG8_WAIT_V(8); PG8_WAIT_L(0); PG8_BAR; PG8_MMA(0, 0, At, B0); PG8_MMA(0, 1, At, B1); PG8_BAR; PG8_SCHED;
;             PG8_LDA(At, 0, 1); PG8_STAGE(PG8_SB(0, 0), b2, voffB); PG8_STAGE(PG8_SB(0, 1), b2 + hstep, voffB); PG8_STAGE(PG8_SA(0, 0), a2, voffA);
;             PG8_WAIT_V(8); PG8_WAIT_L(0); PG8_BAR; PG8_MMA(1, 0, At, B0); PG8_MMA(1, 1, At, B1); PG8_BAR; PG8_SCHED;
;             PG8_LDB(B0, 1, 0); PG8_LDB(B1, 1, 1); PG8_SCHED; PG8_LDA(At, 1, 0); PG8_STAGE(PG8_SA(0, 1), a2 + hstep, voffA);
;             PG8_WAIT_V(8); PG8_WAIT_L(0); PG8_BAR; PG8_MMA(0, 0, At, B0); PG8_MMA(0, 1, At, B1); PG8_BAR; PG8_SCHED;
.Lpeel_hoisted_0:
	ds_read_b128 v[154:157], v149
	ds_read_b128 v[158:161], v149 offset:1024
	ds_read_b128 v[162:165], v149 offset:2048
	ds_read_b128 v[166:169], v149 offset:3072
	ds_read_b128 v[170:173], v150
	ds_read_b128 v[174:177], v150 offset:1024
	ds_read_b128 v[178:181], v150 offset:2048
	ds_read_b128 v[182:185], v150 offset:3072
	s_add_u32 s40, s38, 0xfffc0080
	s_addc_u32 s41, s39, -1
	s_cmp_eq_u32 s68, 12
	s_cselect_b32 s43, s21, s41
	s_cselect_b32 s42, s64, s40
	s_cselect_b32 s41, s19, s67
	s_cselect_b32 s40, s65, s66
	ds_read_b128 v[186:189], v151
	ds_read_b128 v[190:193], v151 offset:1024
	ds_read_b128 v[194:197], v151 offset:2048
	ds_read_b128 v[198:201], v151 offset:3072
	ds_read_b128 v[202:205], v151 offset:4096
	ds_read_b128 v[206:209], v151 offset:5120
	ds_read_b128 v[210:213], v151 offset:6144
	ds_read_b128 v[214:217], v151 offset:7168
	s_waitcnt vmcnt(8)
	s_waitcnt lgkmcnt(0)
	s_barrier
	s_setprio 1
	v_mfma_f32_16x16x32_bf16 v[120:123], v[154:157], v[186:189], 0
	v_mfma_f32_16x16x32_bf16 v[116:119], v[162:165], v[186:189], 0
	v_mfma_f32_16x16x32_bf16 v[108:111], v[154:157], v[194:197], 0
	v_mfma_f32_16x16x32_bf16 v[100:103], v[162:165], v[194:197], 0
	v_mfma_f32_16x16x32_bf16 v[92:95], v[154:157], v[202:205], 0
	v_mfma_f32_16x16x32_bf16 v[84:87], v[162:165], v[202:205], 0
	v_mfma_f32_16x16x32_bf16 v[76:79], v[154:157], v[210:213], 0
	v_mfma_f32_16x16x32_bf16 v[68:71], v[162:165], v[210:213], 0
	v_mfma_f32_16x16x32_bf16 v[120:123], v[158:161], v[190:193], v[120:123]
	v_mfma_f32_16x16x32_bf16 v[116:119], v[166:169], v[190:193], v[116:119]
	v_mfma_f32_16x16x32_bf16 v[108:111], v[158:161], v[198:201], v[108:111]
	v_mfma_f32_16x16x32_bf16 v[100:103], v[166:169], v[198:201], v[100:103]
	v_mfma_f32_16x16x32_bf16 v[92:95], v[158:161], v[206:209], v[92:95]
	v_mfma_f32_16x16x32_bf16 v[84:87], v[166:169], v[206:209], v[84:87]
	v_mfma_f32_16x16x32_bf16 v[76:79], v[158:161], v[214:217], v[76:79]
	v_mfma_f32_16x16x32_bf16 v[68:71], v[166:169], v[214:217], v[68:71]
	v_mfma_f32_16x16x32_bf16 v[124:127], v[170:173], v[186:189], 0
	v_mfma_f32_16x16x32_bf16 v[112:115], v[178:181], v[186:189], 0
	v_mfma_f32_16x16x32_bf16 v[104:107], v[170:173], v[194:197], 0
	v_mfma_f32_16x16x32_bf16 v[96:99], v[178:181], v[194:197], 0
	v_mfma_f32_16x16x32_bf16 v[88:91], v[170:173], v[202:205], 0
	v_mfma_f32_16x16x32_bf16 v[80:83], v[178:181], v[202:205], 0
	v_mfma_f32_16x16x32_bf16 v[72:75], v[170:173], v[210:213], 0
	v_mfma_f32_16x16x32_bf16 v[64:67], v[178:181], v[210:213], 0
	v_mfma_f32_16x16x32_bf16 v[124:127], v[174:177], v[190:193], v[124:127]
	v_mfma_f32_16x16x32_bf16 v[112:115], v[182:185], v[190:193], v[112:115]
	v_mfma_f32_16x16x32_bf16 v[104:107], v[174:177], v[198:201], v[104:107]
	v_mfma_f32_16x16x32_bf16 v[96:99], v[182:185], v[198:201], v[96:99]
	v_mfma_f32_16x16x32_bf16 v[88:91], v[174:177], v[206:209], v[88:91]
	v_mfma_f32_16x16x32_bf16 v[80:83], v[182:185], v[206:209], v[80:83]
	v_mfma_f32_16x16x32_bf16 v[72:75], v[174:177], v[214:217], v[72:75]
	v_mfma_f32_16x16x32_bf16 v[64:67], v[182:185], v[214:217], v[64:67]
	s_barrier
	s_setprio 0
	s_add_i32 s69, s57, s48
	v_lshl_add_u64 v[144:145], s[40:41], 0, v[132:133]
	s_mov_b32 m0, s69
	ds_read_b128 v[186:189], v151 offset:16384
	ds_read_b128 v[190:193], v151 offset:17408
	ds_read_b128 v[194:197], v151 offset:18432
	ds_read_b128 v[198:201], v151 offset:19456
	ds_read_b128 v[202:205], v151 offset:20480
	ds_read_b128 v[206:209], v151 offset:21504
	ds_read_b128 v[210:213], v151 offset:22528
	ds_read_b128 v[214:217], v151 offset:23552
	global_load_lds_dwordx4 v[144:145], off
	s_add_i32 m0, s69, 0x2000
	s_add_u32 s70, s40, 0x40000
	v_lshl_add_u64 v[218:219], s[40:41], 0, v[128:129]
	s_addc_u32 s71, s41, 0
	s_add_i32 s69, s58, s48
	global_load_lds_dwordx4 v[218:219], off
	v_lshl_add_u64 v[220:221], s[70:71], 0, v[132:133]
	s_mov_b32 m0, s69
	v_lshl_add_u64 v[222:223], s[42:43], 0, v[130:131]
	global_load_lds_dwordx4 v[220:221], off
	v_lshl_add_u64 v[220:221], s[70:71], 0, v[128:129]
	s_add_i32 m0, s69, 0x2000
	s_nop 0
	global_load_lds_dwordx4 v[220:221], off
	v_lshl_add_u64 v[220:221], s[42:43], 0, v[134:135]
	s_mov_b32 m0, s37
	s_nop 0
	global_load_lds_dwordx4 v[220:221], off
	s_mov_b32 m0, s50
	s_nop 0
	global_load_lds_dwordx4 v[222:223], off
	s_waitcnt vmcnt(14)
	s_waitcnt lgkmcnt(0)
	s_barrier
	s_setprio 1
	v_mfma_f32_16x16x32_bf16 v[60:63], v[154:157], v[186:189], 0
	v_mfma_f32_16x16x32_bf16 v[52:55], v[162:165], v[186:189], 0
	v_mfma_f32_16x16x32_bf16 v[44:47], v[154:157], v[194:197], 0
	v_mfma_f32_16x16x32_bf16 v[36:39], v[162:165], v[194:197], 0
	v_mfma_f32_16x16x32_bf16 v[28:31], v[154:157], v[202:205], 0
	v_mfma_f32_16x16x32_bf16 v[20:23], v[162:165], v[202:205], 0
	v_mfma_f32_16x16x32_bf16 v[12:15], v[154:157], v[210:213], 0
	v_mfma_f32_16x16x32_bf16 v[4:7], v[162:165], v[210:213], 0
	v_mfma_f32_16x16x32_bf16 v[60:63], v[158:161], v[190:193], v[60:63]
	v_mfma_f32_16x16x32_bf16 v[52:55], v[166:169], v[190:193], v[52:55]
	v_mfma_f32_16x16x32_bf16 v[44:47], v[158:161], v[198:201], v[44:47]
	v_mfma_f32_16x16x32_bf16 v[36:39], v[166:169], v[198:201], v[36:39]
	v_mfma_f32_16x16x32_bf16 v[28:31], v[158:161], v[206:209], v[28:31]
	v_mfma_f32_16x16x32_bf16 v[20:23], v[166:169], v[206:209], v[20:23]
	v_mfma_f32_16x16x32_bf16 v[12:15], v[158:161], v[214:217], v[12:15]
	v_mfma_f32_16x16x32_bf16 v[4:7], v[166:169], v[214:217], v[4:7]
	v_mfma_f32_16x16x32_bf16 v[56:59], v[170:173], v[186:189], 0
	v_mfma_f32_16x16x32_bf16 v[48:51], v[178:181], v[186:189], 0
	v_mfma_f32_16x16x32_bf16 v[40:43], v[170:173], v[194:197], 0
	v_mfma_f32_16x16x32_bf16 v[32:35], v[178:181], v[194:197], 0
	v_mfma_f32_16x16x32_bf16 v[24:27], v[170:173], v[202:205], 0
	v_mfma_f32_16x16x32_bf16 v[16:19], v[178:181], v[202:205], 0
	v_mfma_f32_16x16x32_bf16 v[8:11], v[170:173], v[210:213], 0
	v_mfma_f32_16x16x32_bf16 v[0:3], v[178:181], v[210:213], 0
	v_mfma_f32_16x16x32_bf16 v[56:59], v[174:177], v[190:193], v[56:59]
	v_mfma_f32_16x16x32_bf16 v[48:51], v[182:185], v[190:193], v[48:51]
	v_mfma_f32_16x16x32_bf16 v[40:43], v[174:177], v[198:201], v[40:43]
	v_mfma_f32_16x16x32_bf16 v[32:35], v[182:185], v[198:201], v[32:35]
	v_mfma_f32_16x16x32_bf16 v[24:27], v[174:177], v[206:209], v[24:27]
	v_mfma_f32_16x16x32_bf16 v[16:19], v[182:185], v[206:209], v[16:19]
	v_mfma_f32_16x16x32_bf16 v[8:11], v[174:177], v[214:217], v[8:11]
	v_mfma_f32_16x16x32_bf16 v[0:3], v[182:185], v[214:217], v[0:3]
	s_barrier
; #define PG8_STAGE(bufoff, gbase, voff) do { _Pragma("unroll") for (int _i = 0; _i < 2; ++_i) \
;         __builtin_amdgcn_global_load_lds((const unsigned*)((const char*)(gbase) + (voff)[_i]), (PG8_LAS unsigned*)(lds + (bufoff) + ldsw + _i * 8192), 16, 0, 0); } while (0)
; #define PG8_LDA(dst, b, h) do { _Pragma("unroll") for (int m = 0; m < 4; ++m) _Pragma("unroll") for (int k = 0; k < 2; ++k) dst[m][k] = *(const PG8_LAS bf16x8*)(lds + PG8_SA(b, h) + aoff + m * 2048 + k * 1024); } while (0)
; #define PG8_LDB(dst, b, h) do { _Pragma("unroll") for (int n = 0; n < 2; ++n) _Pragma("unroll") for (int k = 0; k < 2; ++k) dst[n][k] = *(const PG8_LAS bf16x8*)(lds + PG8_SB(b, h) + boff + n * 2048 + k * 1024); } while (0)
; #define PG8_MMA(ai, bj, At, Bt) do { __builtin_amdgcn_s_setprio(1); _Pragma("unroll") for (int m = 0; m < 4; ++m) _Pragma("unroll") for (int n = 0; n < 2; ++n) _Pragma("unroll") for (int k = 0; k < 2; ++k) \
;         acc[ai][bj][m][n] = __builtin_amdgcn_mfma_f32_16x16x32_bf16(Bt[n][k], At[m][k], acc[ai][bj][m][n], 0, 0, 0); __builtin_amdgcn_s_setprio(0); } while (0)
; #define PG8_WAIT_V(n) asm volatile("s_waitcnt vmcnt(" #n ")" ::: "memory")
; #define PG8_WAIT_L(n) asm volatile("s_waitcnt lgkmcnt(" #n ")" ::: "memory")
; #define PG8_BAR __builtin_amdgcn_s_barrier()
; #define PG8_SCHED __builtin_amdgcn_sched_barrier(0)
; template <class Epi, class Sched, bool ALIGN_EPI = false, bool SP2 = false>
; __device__ __forceinline__ void gemm_phase(PG8_LAS unsigned char* lds, const Gemm g, const Sched& S, const Epi& E) {
;     ...
;             PG8_LDB(B0, 1, 0); PG8_LDB(B1, 1, 1); PG8_SCHED; PG8_LDA(At, 1, 0); PG8_STAGE(PG8_SA(0, 1), a2 + hstep, voffA);
;             PG8_WAIT_V(8); PG8_WAIT_L(0); PG8_BAR; PG8_MMA(0, 0, At, B0); PG8_MMA(0, 1, At, B1); PG8_BAR; PG8_SCHED;
;             PG8_LDA(At, 1, 1); PG8_STAGE(PG8_SB(1, 0), b3, voffB); PG8_STAGE(PG8_SB(1, 1), b3 + hstep, voffB); PG8_STAGE(PG8_SA(1, 0), a3, voffA);
;             PG8_WAIT_V(8); PG8_WAIT_L(0); PG8_BAR; PG8_MMA(1, 0, At, B0); PG8_MMA(1, 1, At, B1); PG8_BAR; PG8_SCHED;
	s_setprio 0
	s_add_i32 s69, 0, 0x18000
	v_add_u32_e32 v153, s69, v147
	s_add_i32 s70, 0, 0x1c000
	ds_read_b128 v[154:157], v153
	ds_read_b128 v[158:161], v153 offset:1024
	ds_read_b128 v[162:165], v153 offset:2048
	ds_read_b128 v[166:169], v153 offset:3072
	v_add_u32_e32 v153, s70, v147
	ds_read_b128 v[170:173], v153
	ds_read_b128 v[174:177], v153 offset:1024
	ds_read_b128 v[178:181], v153 offset:2048
	ds_read_b128 v[182:185], v153 offset:3072
	s_add_u32 s42, s42, 0x40000
	s_addc_u32 s43, s43, 0
	s_mov_b32 m0, s51
	v_lshl_add_u64 v[224:225], s[42:43], 0, v[134:135]
	ds_read_b128 v[186:189], v151 offset:32768
	ds_read_b128 v[190:193], v151 offset:33792
	ds_read_b128 v[194:197], v151 offset:34816
	ds_read_b128 v[198:201], v151 offset:35840
	ds_read_b128 v[202:205], v151 offset:36864
	ds_read_b128 v[206:209], v151 offset:37888
	ds_read_b128 v[210:213], v151 offset:38912
	ds_read_b128 v[214:217], v151 offset:39936
	global_load_lds_dwordx4 v[224:225], off
	v_lshl_add_u64 v[224:225], s[42:43], 0, v[130:131]
	s_mov_b32 m0, s52
	s_nop 0
	global_load_lds_dwordx4 v[224:225], off
	s_waitcnt vmcnt(16)
	s_waitcnt lgkmcnt(0)
	s_barrier
	s_setprio 1
	v_mfma_f32_16x16x32_bf16 v[120:123], v[154:157], v[186:189], v[120:123]
	v_mfma_f32_16x16x32_bf16 v[116:119], v[162:165], v[186:189], v[116:119]
	v_mfma_f32_16x16x32_bf16 v[108:111], v[154:157], v[194:197], v[108:111]
	v_mfma_f32_16x16x32_bf16 v[100:103], v[162:165], v[194:197], v[100:103]
	v_mfma_f32_16x16x32_bf16 v[92:95], v[154:157], v[202:205], v[92:95]
	v_mfma_f32_16x16x32_bf16 v[84:87], v[162:165], v[202:205], v[84:87]
	v_mfma_f32_16x16x32_bf16 v[76:79], v[154:157], v[210:213], v[76:79]
	v_mfma_f32_16x16x32_bf16 v[68:71], v[162:165], v[210:213], v[68:71]
	v_mfma_f32_16x16x32_bf16 v[120:123], v[158:161], v[190:193], v[120:123]
	v_mfma_f32_16x16x32_bf16 v[116:119], v[166:169], v[190:193], v[116:119]
	v_mfma_f32_16x16x32_bf16 v[108:111], v[158:161], v[198:201], v[108:111]
	v_mfma_f32_16x16x32_bf16 v[100:103], v[166:169], v[198:201], v[100:103]
	v_mfma_f32_16x16x32_bf16 v[92:95], v[158:161], v[206:209], v[92:95]
	v_mfma_f32_16x16x32_bf16 v[84:87], v[166:169], v[206:209], v[84:87]
	v_mfma_f32_16x16x32_bf16 v[76:79], v[158:161], v[214:217], v[76:79]
	v_mfma_f32_16x16x32_bf16 v[68:71], v[166:169], v[214:217], v[68:71]
	v_mfma_f32_16x16x32_bf16 v[124:127], v[170:173], v[186:189], v[124:127]
	v_mfma_f32_16x16x32_bf16 v[112:115], v[178:181], v[186:189], v[112:115]
	v_mfma_f32_16x16x32_bf16 v[104:107], v[170:173], v[194:197], v[104:107]
	v_mfma_f32_16x16x32_bf16 v[96:99], v[178:181], v[194:197], v[96:99]
	v_mfma_f32_16x16x32_bf16 v[88:91], v[170:173], v[202:205], v[88:91]
	v_mfma_f32_16x16x32_bf16 v[80:83], v[178:181], v[202:205], v[80:83]
	v_mfma_f32_16x16x32_bf16 v[72:75], v[170:173], v[210:213], v[72:75]
	v_mfma_f32_16x16x32_bf16 v[64:67], v[178:181], v[210:213], v[64:67]
	v_mfma_f32_16x16x32_bf16 v[124:127], v[174:177], v[190:193], v[124:127]
	v_mfma_f32_16x16x32_bf16 v[112:115], v[182:185], v[190:193], v[112:115]
	v_mfma_f32_16x16x32_bf16 v[104:107], v[174:177], v[198:201], v[104:107]
	v_mfma_f32_16x16x32_bf16 v[96:99], v[182:185], v[198:201], v[96:99]
	v_mfma_f32_16x16x32_bf16 v[88:91], v[174:177], v[206:209], v[88:91]
	v_mfma_f32_16x16x32_bf16 v[80:83], v[182:185], v[206:209], v[80:83]
	v_mfma_f32_16x16x32_bf16 v[72:75], v[174:177], v[214:217], v[72:75]
	v_mfma_f32_16x16x32_bf16 v[64:67], v[182:185], v[214:217], v[64:67]
	s_barrier
	s_setprio 0
	s_add_i32 s42, s69, s48
	v_lshl_add_u64 v[144:145], v[144:145], 0, s[14:15]
	s_mov_b32 m0, s42
	ds_read_b128 v[186:189], v151 offset:49152
	ds_read_b128 v[190:193], v151 offset:50176
	ds_read_b128 v[194:197], v151 offset:51200
	ds_read_b128 v[198:201], v151 offset:52224
	ds_read_b128 v[202:205], v151 offset:53248
	ds_read_b128 v[206:209], v151 offset:54272
	ds_read_b128 v[210:213], v151 offset:55296
	ds_read_b128 v[214:217], v151 offset:56320
	global_load_lds_dwordx4 v[144:145], off
	s_add_i32 m0, s42, 0x2000
	s_add_u32 s40, s40, 0x40080
	v_lshl_add_u64 v[144:145], v[218:219], 0, s[14:15]
	s_addc_u32 s41, s41, 0
	s_add_i32 s42, s70, s48
	global_load_lds_dwordx4 v[144:145], off
	v_lshl_add_u64 v[144:145], s[40:41], 0, v[132:133]
	s_mov_b32 m0, s42
	s_nop 0
	global_load_lds_dwordx4 v[144:145], off
	v_lshl_add_u64 v[144:145], s[40:41], 0, v[128:129]
	s_add_i32 m0, s42, 0x2000
	s_nop 0
	global_load_lds_dwordx4 v[144:145], off
	v_lshl_add_u64 v[144:145], v[220:221], 0, s[14:15]
	s_mov_b32 m0, s54
	s_nop 0
	global_load_lds_dwordx4 v[144:145], off
	v_lshl_add_u64 v[144:145], v[222:223], 0, s[14:15]
	s_mov_b32 m0, s55
	s_nop 0
	global_load_lds_dwordx4 v[144:145], off
	s_and_b64 vcc, exec, s[16:17]
	s_cbranch_vccnz .Llatew_0
	s_waitcnt vmcnt(8)
; #define PG8_MMA(ai, bj, At, Bt) do { __builtin_amdgcn_s_setprio(1); _Pragma("unroll") for (int m = 0; m < 4; ++m) _Pragma("unroll") for (int n = 0; n < 2; ++n) _Pragma("unroll") for (int k = 0; k < 2; ++k) \
;         acc[ai][bj][m][n] = __builtin_amdgcn_mfma_f32_16x16x32_bf16(Bt[n][k], At[m][k], acc[ai][bj][m][n], 0, 0, 0); __builtin_amdgcn_s_setprio(0); } while (0)
; #define PG8_WAIT_V(n) asm volatile("s_waitcnt vmcnt(" #n ")" ::: "memory")
; #define PG8_WAIT_L(n) asm volatile("s_waitcnt lgkmcnt(" #n ")" ::: "memory")
; #define PG8_BAR __builtin_amdgcn_s_barrier()
; #define PG8_SCHED __builtin_amdgcn_sched_barrier(0)
; template <class Epi, class Sched, bool ALIGN_EPI = false, bool SP2 = false>
; __device__ __forceinline__ void gemm_phase(PG8_LAS unsigned char* lds, const Gemm g, const Sched& S, const Epi& E) {
;     ...
;             PG8_WAIT_V(8); PG8_WAIT_L(0); PG8_BAR; PG8_MMA(1, 0, At, B0); PG8_MMA(1, 1, At, B1); PG8_BAR; PG8_SCHED;
.Llatew_0:
	s_waitcnt lgkmcnt(0)
	s_barrier
	s_setprio 1
	v_mfma_f32_16x16x32_bf16 v[60:63], v[154:157], v[186:189], v[60:63]
	v_mfma_f32_16x16x32_bf16 v[52:55], v[162:165], v[186:189], v[52:55]
	v_mfma_f32_16x16x32_bf16 v[44:47], v[154:157], v[194:197], v[44:47]
	v_mfma_f32_16x16x32_bf16 v[36:39], v[162:165], v[194:197], v[36:39]
	v_mfma_f32_16x16x32_bf16 v[28:31], v[154:157], v[202:205], v[28:31]
	v_mfma_f32_16x16x32_bf16 v[20:23], v[162:165], v[202:205], v[20:23]
	v_mfma_f32_16x16x32_bf16 v[12:15], v[154:157], v[210:213], v[12:15]
	v_mfma_f32_16x16x32_bf16 v[4:7], v[162:165], v[210:213], v[4:7]
	v_mfma_f32_16x16x32_bf16 v[60:63], v[158:161], v[190:193], v[60:63]
	v_mfma_f32_16x16x32_bf16 v[52:55], v[166:169], v[190:193], v[52:55]
	v_mfma_f32_16x16x32_bf16 v[44:47], v[158:161], v[198:201], v[44:47]
	v_mfma_f32_16x16x32_bf16 v[36:39], v[166:169], v[198:201], v[36:39]
	v_mfma_f32_16x16x32_bf16 v[28:31], v[158:161], v[206:209], v[28:31]
	v_mfma_f32_16x16x32_bf16 v[20:23], v[166:169], v[206:209], v[20:23]
	v_mfma_f32_16x16x32_bf16 v[12:15], v[158:161], v[214:217], v[12:15]
	v_mfma_f32_16x16x32_bf16 v[4:7], v[166:169], v[214:217], v[4:7]
	v_mfma_f32_16x16x32_bf16 v[56:59], v[170:173], v[186:189], v[56:59]
	v_mfma_f32_16x16x32_bf16 v[48:51], v[178:181], v[186:189], v[48:51]
	v_mfma_f32_16x16x32_bf16 v[40:43], v[170:173], v[194:197], v[40:43]
	v_mfma_f32_16x16x32_bf16 v[32:35], v[178:181], v[194:197], v[32:35]
	v_mfma_f32_16x16x32_bf16 v[24:27], v[170:173], v[202:205], v[24:27]
	v_mfma_f32_16x16x32_bf16 v[16:19], v[178:181], v[202:205], v[16:19]
	v_mfma_f32_16x16x32_bf16 v[8:11], v[170:173], v[210:213], v[8:11]
	v_mfma_f32_16x16x32_bf16 v[0:3], v[178:181], v[210:213], v[0:3]
	v_mfma_f32_16x16x32_bf16 v[56:59], v[174:177], v[190:193], v[56:59]
	v_mfma_f32_16x16x32_bf16 v[48:51], v[182:185], v[190:193], v[48:51]
	v_mfma_f32_16x16x32_bf16 v[40:43], v[174:177], v[198:201], v[40:43]
	v_mfma_f32_16x16x32_bf16 v[32:35], v[182:185], v[198:201], v[32:35]
	v_mfma_f32_16x16x32_bf16 v[24:27], v[174:177], v[206:209], v[24:27]
	v_mfma_f32_16x16x32_bf16 v[16:19], v[182:185], v[206:209], v[16:19]
	v_mfma_f32_16x16x32_bf16 v[8:11], v[174:177], v[214:217], v[8:11]
	v_mfma_f32_16x16x32_bf16 v[0:3], v[182:185], v[214:217], v[0:3]
	s_waitcnt vmcnt(8)
	s_barrier
	s_setprio 0
	s_add_i32 s68, s68, 2
	s_add_u32 s38, s38, 0x100
	s_addc_u32 s39, s39, 0
	s_add_u32 s66, s66, 0x100
	s_addc_u32 s67, s67, 0

; #define PG8_STAGE(bufoff, gbase, voff) do { _Pragma("unroll") for (int _i = 0; _i < 2; ++_i) \
;         __builtin_amdgcn_global_load_lds((const unsigned*)((const char*)(gbase) + (voff)[_i]), (PG8_LAS unsigned*)(lds + (bufoff) + ldsw + _i * 8192), 16, 0, 0); } while (0)
; #define PG8_LDA(dst, b, h) do { _Pragma("unroll") for (int m = 0; m < 4; ++m) _Pragma("unroll") for (int k = 0; k < 2; ++k) dst[m][k] = *(const PG8_LAS bf16x8*)(lds + PG8_SA(b, h) + aoff + m * 2048 + k * 1024); } while (0)
; #define PG8_LDB(dst, b, h) do { _Pragma("unroll") for (int n = 0; n < 2; ++n) _Pragma("unroll") for (int k = 0; k < 2; ++k) dst[n][k] = *(const PG8_LAS bf16x8*)(lds + PG8_SB(b, h) + boff + n * 2048 + k * 1024); } while (0)
; #define PG8_MMA(ai, bj, At, Bt) do { __builtin_amdgcn_s_setprio(1); _Pragma("unroll") for (int m = 0; m < 4; ++m) _Pragma("unroll") for (int n = 0; n < 2; ++n) _Pragma("unroll") for (int k = 0; k < 2; ++k) \
;         acc[ai][bj][m][n] = __builtin_amdgcn_mfma_f32_16x16x32_bf16(Bt[n][k], At[m][k], acc[ai][bj][m][n], 0, 0, 0); __builtin_amdgcn_s_setprio(0); } while (0)
; #define PG8_WAIT_V(n) asm volatile("s_waitcnt vmcnt(" #n ")" ::: "memory")
; #define PG8_WAIT_L(n) asm volatile("s_waitcnt lgkmcnt(" #n ")" ::: "memory")
; #define PG8_BAR __builtin_amdgcn_s_barrier()
; #define PG8_SCHED __builtin_amdgcn_sched_barrier(0)
; template <class Epi, class Sched, bool ALIGN_EPI = false, bool SP2 = false>
; __device__ __forceinline__ void gemm_phase(PG8_LAS unsigned char* lds, const Gemm g, const Sched& S, const Epi& E) {
;     ...
;             PG8_LDB(B0, 0, 0); PG8_LDB(B1, 0, 1); PG8_SCHED; PG8_LDA(At, 0, 0); PG8_STAGE(PG8_SA(1, 1), a1 + hstep, voffA);
;             PG8_WAIT_V(8); PG8_WAIT_L(0); PG8_BAR; PG8_MMA(0, 0, At, B0); PG8_MMA(0, 1, At, B1); PG8_BAR; PG8_SCHED;
;             PG8_LDA(At, 0, 1); PG8_STAGE(PG8_SB(0, 0), b2, voffB); PG8_STAGE(PG8_SB(0, 1), b2 + hstep, voffB); PG8_STAGE(PG8_SA(0, 0), a2, voffA);
;             PG8_WAIT_V(8); PG8_WAIT_L(0); PG8_BAR; PG8_MMA(1, 0, At, B0); PG8_MMA(1, 1, At, B1); PG8_BAR; PG8_SCHED;
.Lpeel_hoisted_1:
	ds_read_b128 v[154:157], v149
	ds_read_b128 v[158:161], v149 offset:1024
	ds_read_b128 v[162:165], v149 offset:2048
	ds_read_b128 v[166:169], v149 offset:3072
	ds_read_b128 v[170:173], v150
	ds_read_b128 v[174:177], v150 offset:1024
	ds_read_b128 v[178:181], v150 offset:2048
	ds_read_b128 v[182:185], v150 offset:3072
	s_add_u32 s40, s38, 0xfffc0080
	s_addc_u32 s41, s39, -1
	s_cmp_eq_u32 s68, 12
	s_cselect_b32 s43, s21, s41
	s_cselect_b32 s42, s64, s40
	s_cselect_b32 s41, s19, s67
	s_cselect_b32 s40, s65, s66
	ds_read_b128 v[186:189], v151
	ds_read_b128 v[190:193], v151 offset:1024
	ds_read_b128 v[194:197], v151 offset:2048
	ds_read_b128 v[198:201], v151 offset:3072
	ds_read_b128 v[202:205], v151 offset:4096
	ds_read_b128 v[206:209], v151 offset:5120
	ds_read_b128 v[210:213], v151 offset:6144
	ds_read_b128 v[214:217], v151 offset:7168
	s_waitcnt vmcnt(8)
	s_waitcnt lgkmcnt(0)
	s_barrier
	s_setprio 1
	v_mfma_f32_16x16x32_bf16 v[120:123], v[154:157], v[186:189], 0
	v_mfma_f32_16x16x32_bf16 v[116:119], v[162:165], v[186:189], 0
	v_mfma_f32_16x16x32_bf16 v[108:111], v[154:157], v[194:197], 0
	v_mfma_f32_16x16x32_bf16 v[100:103], v[162:165], v[194:197], 0
	v_mfma_f32_16x16x32_bf16 v[92:95], v[154:157], v[202:205], 0
	v_mfma_f32_16x16x32_bf16 v[84:87], v[162:165], v[202:205], 0
	v_mfma_f32_16x16x32_bf16 v[76:79], v[154:157], v[210:213], 0
	v_mfma_f32_16x16x32_bf16 v[68:71], v[162:165], v[210:213], 0
	v_mfma_f32_16x16x32_bf16 v[120:123], v[158:161], v[190:193], v[120:123]
	v_mfma_f32_16x16x32_bf16 v[116:119], v[166:169], v[190:193], v[116:119]
	v_mfma_f32_16x16x32_bf16 v[108:111], v[158:161], v[198:201], v[108:111]
	v_mfma_f32_16x16x32_bf16 v[100:103], v[166:169], v[198:201], v[100:103]
	v_mfma_f32_16x16x32_bf16 v[92:95], v[158:161], v[206:209], v[92:95]
	v_mfma_f32_16x16x32_bf16 v[84:87], v[166:169], v[206:209], v[84:87]
	v_mfma_f32_16x16x32_bf16 v[76:79], v[158:161], v[214:217], v[76:79]
	v_mfma_f32_16x16x32_bf16 v[68:71], v[166:169], v[214:217], v[68:71]
	v_mfma_f32_16x16x32_bf16 v[124:127], v[170:173], v[186:189], 0
	v_mfma_f32_16x16x32_bf16 v[112:115], v[178:181], v[186:189], 0
	v_mfma_f32_16x16x32_bf16 v[104:107], v[170:173], v[194:197], 0
	v_mfma_f32_16x16x32_bf16 v[96:99], v[178:181], v[194:197], 0
	v_mfma_f32_16x16x32_bf16 v[88:91], v[170:173], v[202:205], 0
	v_mfma_f32_16x16x32_bf16 v[80:83], v[178:181], v[202:205], 0
	v_mfma_f32_16x16x32_bf16 v[72:75], v[170:173], v[210:213], 0
	v_mfma_f32_16x16x32_bf16 v[64:67], v[178:181], v[210:213], 0
	v_mfma_f32_16x16x32_bf16 v[124:127], v[174:177], v[190:193], v[124:127]
	v_mfma_f32_16x16x32_bf16 v[112:115], v[182:185], v[190:193], v[112:115]
	v_mfma_f32_16x16x32_bf16 v[104:107], v[174:177], v[198:201], v[104:107]
	v_mfma_f32_16x16x32_bf16 v[96:99], v[182:185], v[198:201], v[96:99]
	v_mfma_f32_16x16x32_bf16 v[88:91], v[174:177], v[206:209], v[88:91]
	v_mfma_f32_16x16x32_bf16 v[80:83], v[182:185], v[206:209], v[80:83]
	v_mfma_f32_16x16x32_bf16 v[72:75], v[174:177], v[214:217], v[72:75]
	v_mfma_f32_16x16x32_bf16 v[64:67], v[182:185], v[214:217], v[64:67]
	s_barrier
	s_setprio 0
	s_add_i32 s69, s57, s48
	v_lshl_add_u64 v[144:145], s[40:41], 0, v[132:133]
	s_mov_b32 m0, s69
	ds_read_b128 v[186:189], v151 offset:16384
	ds_read_b128 v[190:193], v151 offset:17408
	ds_read_b128 v[194:197], v151 offset:18432
	ds_read_b128 v[198:201], v151 offset:19456
	ds_read_b128 v[202:205], v151 offset:20480
	ds_read_b128 v[206:209], v151 offset:21504
	ds_read_b128 v[210:213], v151 offset:22528
	ds_read_b128 v[214:217], v151 offset:23552
	global_load_lds_dwordx4 v[144:145], off
	s_add_i32 m0, s69, 0x2000
	s_add_u32 s70, s40, 0x40000
	v_lshl_add_u64 v[218:219], s[40:41], 0, v[128:129]
	s_addc_u32 s71, s41, 0
	s_add_i32 s69, s58, s48
	global_load_lds_dwordx4 v[218:219], off
	v_lshl_add_u64 v[220:221], s[70:71], 0, v[132:133]
	s_mov_b32 m0, s69
	v_lshl_add_u64 v[222:223], s[42:43], 0, v[130:131]
	global_load_lds_dwordx4 v[220:221], off
	v_lshl_add_u64 v[220:221], s[70:71], 0, v[128:129]
	s_add_i32 m0, s69, 0x2000
	s_nop 0
	global_load_lds_dwordx4 v[220:221], off
	v_lshl_add_u64 v[220:221], s[42:43], 0, v[134:135]
	s_mov_b32 m0, s37
	s_nop 0
	global_load_lds_dwordx4 v[220:221], off
	s_mov_b32 m0, s50
	s_nop 0
	global_load_lds_dwordx4 v[222:223], off
	s_waitcnt vmcnt(14)
	s_waitcnt lgkmcnt(0)
	s_barrier
	s_setprio 1
	v_mfma_f32_16x16x32_bf16 v[60:63], v[154:157], v[186:189], 0
	v_mfma_f32_16x16x32_bf16 v[52:55], v[162:165], v[186:189], 0
	v_mfma_f32_16x16x32_bf16 v[44:47], v[154:157], v[194:197], 0
	v_mfma_f32_16x16x32_bf16 v[36:39], v[162:165], v[194:197], 0
	v_mfma_f32_16x16x32_bf16 v[28:31], v[154:157], v[202:205], 0
	v_mfma_f32_16x16x32_bf16 v[20:23], v[162:165], v[202:205], 0
	v_mfma_f32_16x16x32_bf16 v[12:15], v[154:157], v[210:213], 0
	v_mfma_f32_16x16x32_bf16 v[4:7], v[162:165], v[210:213], 0
	v_mfma_f32_16x16x32_bf16 v[60:63], v[158:161], v[190:193], v[60:63]
	v_mfma_f32_16x16x32_bf16 v[52:55], v[166:169], v[190:193], v[52:55]
	v_mfma_f32_16x16x32_bf16 v[44:47], v[158:161], v[198:201], v[44:47]
	v_mfma_f32_16x16x32_bf16 v[36:39], v[166:169], v[198:201], v[36:39]
	v_mfma_f32_16x16x32_bf16 v[28:31], v[158:161], v[206:209], v[28:31]
	v_mfma_f32_16x16x32_bf16 v[20:23], v[166:169], v[206:209], v[20:23]
	v_mfma_f32_16x16x32_bf16 v[12:15], v[158:161], v[214:217], v[12:15]
	v_mfma_f32_16x16x32_bf16 v[4:7], v[166:169], v[214:217], v[4:7]
	v_mfma_f32_16x16x32_bf16 v[56:59], v[170:173], v[186:189], 0
	v_mfma_f32_16x16x32_bf16 v[48:51], v[178:181], v[186:189], 0
	v_mfma_f32_16x16x32_bf16 v[40:43], v[170:173], v[194:197], 0
	v_mfma_f32_16x16x32_bf16 v[32:35], v[178:181], v[194:197], 0
	v_mfma_f32_16x16x32_bf16 v[24:27], v[170:173], v[202:205], 0
	v_mfma_f32_16x16x32_bf16 v[16:19], v[178:181], v[202:205], 0
	v_mfma_f32_16x16x32_bf16 v[8:11], v[170:173], v[210:213], 0
	v_mfma_f32_16x16x32_bf16 v[0:3], v[178:181], v[210:213], 0
	v_mfma_f32_16x16x32_bf16 v[56:59], v[174:177], v[190:193], v[56:59]
	v_mfma_f32_16x16x32_bf16 v[48:51], v[182:185], v[190:193], v[48:51]
	v_mfma_f32_16x16x32_bf16 v[40:43], v[174:177], v[198:201], v[40:43]
	v_mfma_f32_16x16x32_bf16 v[32:35], v[182:185], v[198:201], v[32:35]
	v_mfma_f32_16x16x32_bf16 v[24:27], v[174:177], v[206:209], v[24:27]
	v_mfma_f32_16x16x32_bf16 v[16:19], v[182:185], v[206:209], v[16:19]
	v_mfma_f32_16x16x32_bf16 v[8:11], v[174:177], v[214:217], v[8:11]
	v_mfma_f32_16x16x32_bf16 v[0:3], v[182:185], v[214:217], v[0:3]
	s_barrier
; #define PG8_STAGE(bufoff, gbase, voff) do { _Pragma("unroll") for (int _i = 0; _i < 2; ++_i) \
;         __builtin_amdgcn_global_load_lds((const unsigned*)((const char*)(gbase) + (voff)[_i]), (PG8_LAS unsigned*)(lds + (bufoff) + ldsw + _i * 8192), 16, 0, 0); } while (0)
; #define PG8_LDA(dst, b, h) do { _Pragma("unroll") for (int m = 0; m < 4; ++m) _Pragma("unroll") for (int k = 0; k < 2; ++k) dst[m][k] = *(const PG8_LAS bf16x8*)(lds + PG8_SA(b, h) + aoff + m * 2048 + k * 1024); } while (0)
; #define PG8_LDB(dst, b, h) do { _Pragma("unroll") for (int n = 0; n < 2; ++n) _Pragma("unroll") for (int k = 0; k < 2; ++k) dst[n][k] = *(const PG8_LAS bf16x8*)(lds + PG8_SB(b, h) + boff + n * 2048 + k * 1024); } while (0)
; #define PG8_MMA(ai, bj, At, Bt) do { __builtin_amdgcn_s_setprio(1); _Pragma("unroll") for (int m = 0; m < 4; ++m) _Pragma("unroll") for (int n = 0; n < 2; ++n) _Pragma("unroll") for (int k = 0; k < 2; ++k) \
;         acc[ai][bj][m][n] = __builtin_amdgcn_mfma_f32_16x16x32_bf16(Bt[n][k], At[m][k], acc[ai][bj][m][n], 0, 0, 0); __builtin_amdgcn_s_setprio(0); } while (0)
; #define PG8_WAIT_V(n) asm volatile("s_waitcnt vmcnt(" #n ")" ::: "memory")
; #define PG8_WAIT_L(n) asm volatile("s_waitcnt lgkmcnt(" #n ")" ::: "memory")
; #define PG8_BAR __builtin_amdgcn_s_barrier()
; #define PG8_SCHED __builtin_amdgcn_sched_barrier(0)
; template <class Epi, class Sched, bool ALIGN_EPI = false, bool SP2 = false>
; __device__ __forceinline__ void gemm_phase(PG8_LAS unsigned char* lds, const Gemm g, const Sched& S, const Epi& E) {
;     ...
;             PG8_LDB(B0, 1, 0); PG8_LDB(B1, 1, 1); PG8_SCHED; PG8_LDA(At, 1, 0); PG8_STAGE(PG8_SA(0, 1), a2 + hstep, voffA);
;             PG8_WAIT_V(8); PG8_WAIT_L(0); PG8_BAR; PG8_MMA(0, 0, At, B0); PG8_MMA(0, 1, At, B1); PG8_BAR; PG8_SCHED;
;             PG8_LDA(At, 1, 1); PG8_STAGE(PG8_SB(1, 0), b3, voffB); PG8_STAGE(PG8_SB(1, 1), b3 + hstep, voffB); PG8_STAGE(PG8_SA(1, 0), a3, voffA);
;             PG8_WAIT_V(8); PG8_WAIT_L(0); PG8_BAR; PG8_MMA(1, 0, At, B0); PG8_MMA(1, 1, At, B1); PG8_BAR; PG8_SCHED;
	s_setprio 0
	s_add_i32 s69, 0, 0x18000
	v_add_u32_e32 v153, s69, v147
	s_add_i32 s70, 0, 0x1c000
	ds_read_b128 v[154:157], v153
	ds_read_b128 v[158:161], v153 offset:1024
	ds_read_b128 v[162:165], v153 offset:2048
	ds_read_b128 v[166:169], v153 offset:3072
	v_add_u32_e32 v153, s70, v147
	ds_read_b128 v[170:173], v153
	ds_read_b128 v[174:177], v153 offset:1024
	ds_read_b128 v[178:181], v153 offset:2048
	ds_read_b128 v[182:185], v153 offset:3072
	s_add_u32 s42, s42, 0x40000
	s_addc_u32 s43, s43, 0
	s_mov_b32 m0, s51
	v_lshl_add_u64 v[224:225], s[42:43], 0, v[134:135]
	ds_read_b128 v[186:189], v151 offset:32768
	ds_read_b128 v[190:193], v151 offset:33792
	ds_read_b128 v[194:197], v151 offset:34816
	ds_read_b128 v[198:201], v151 offset:35840
	ds_read_b128 v[202:205], v151 offset:36864
	ds_read_b128 v[206:209], v151 offset:37888
	ds_read_b128 v[210:213], v151 offset:38912
	ds_read_b128 v[214:217], v151 offset:39936
	global_load_lds_dwordx4 v[224:225], off
	v_lshl_add_u64 v[224:225], s[42:43], 0, v[130:131]
	s_mov_b32 m0, s52
	s_nop 0
	global_load_lds_dwordx4 v[224:225], off
	s_waitcnt vmcnt(16)
	s_waitcnt lgkmcnt(0)
	s_barrier
	s_setprio 1
	v_mfma_f32_16x16x32_bf16 v[120:123], v[154:157], v[186:189], v[120:123]
	v_mfma_f32_16x16x32_bf16 v[116:119], v[162:165], v[186:189], v[116:119]
	v_mfma_f32_16x16x32_bf16 v[108:111], v[154:157], v[194:197], v[108:111]
	v_mfma_f32_16x16x32_bf16 v[100:103], v[162:165], v[194:197], v[100:103]
	v_mfma_f32_16x16x32_bf16 v[92:95], v[154:157], v[202:205], v[92:95]
	v_mfma_f32_16x16x32_bf16 v[84:87], v[162:165], v[202:205], v[84:87]
	v_mfma_f32_16x16x32_bf16 v[76:79], v[154:157], v[210:213], v[76:79]
	v_mfma_f32_16x16x32_bf16 v[68:71], v[162:165], v[210:213], v[68:71]
	v_mfma_f32_16x16x32_bf16 v[120:123], v[158:161], v[190:193], v[120:123]
	v_mfma_f32_16x16x32_bf16 v[116:119], v[166:169], v[190:193], v[116:119]
	v_mfma_f32_16x16x32_bf16 v[108:111], v[158:161], v[198:201], v[108:111]
	v_mfma_f32_16x16x32_bf16 v[100:103], v[166:169], v[198:201], v[100:103]
	v_mfma_f32_16x16x32_bf16 v[92:95], v[158:161], v[206:209], v[92:95]
	v_mfma_f32_16x16x32_bf16 v[84:87], v[166:169], v[206:209], v[84:87]
	v_mfma_f32_16x16x32_bf16 v[76:79], v[158:161], v[214:217], v[76:79]
	v_mfma_f32_16x16x32_bf16 v[68:71], v[166:169], v[214:217], v[68:71]
	v_mfma_f32_16x16x32_bf16 v[124:127], v[170:173], v[186:189], v[124:127]
	v_mfma_f32_16x16x32_bf16 v[112:115], v[178:181], v[186:189], v[112:115]
	v_mfma_f32_16x16x32_bf16 v[104:107], v[170:173], v[194:197], v[104:107]
	v_mfma_f32_16x16x32_bf16 v[96:99], v[178:181], v[194:197], v[96:99]
	v_mfma_f32_16x16x32_bf16 v[88:91], v[170:173], v[202:205], v[88:91]
	v_mfma_f32_16x16x32_bf16 v[80:83], v[178:181], v[202:205], v[80:83]
	v_mfma_f32_16x16x32_bf16 v[72:75], v[170:173], v[210:213], v[72:75]
	v_mfma_f32_16x16x32_bf16 v[64:67], v[178:181], v[210:213], v[64:67]
	v_mfma_f32_16x16x32_bf16 v[124:127], v[174:177], v[190:193], v[124:127]
	v_mfma_f32_16x16x32_bf16 v[112:115], v[182:185], v[190:193], v[112:115]
	v_mfma_f32_16x16x32_bf16 v[104:107], v[174:177], v[198:201], v[104:107]
	v_mfma_f32_16x16x32_bf16 v[96:99], v[182:185], v[198:201], v[96:99]
	v_mfma_f32_16x16x32_bf16 v[88:91], v[174:177], v[206:209], v[88:91]
	v_mfma_f32_16x16x32_bf16 v[80:83], v[182:185], v[206:209], v[80:83]
	v_mfma_f32_16x16x32_bf16 v[72:75], v[174:177], v[214:217], v[72:75]
	v_mfma_f32_16x16x32_bf16 v[64:67], v[182:185], v[214:217], v[64:67]
	s_barrier
	s_setprio 0
	s_add_i32 s42, s69, s48
	v_lshl_add_u64 v[144:145], v[144:145], 0, s[14:15]
	s_mov_b32 m0, s42
	ds_read_b128 v[186:189], v151 offset:49152
	ds_read_b128 v[190:193], v151 offset:50176
	ds_read_b128 v[194:197], v151 offset:51200
	ds_read_b128 v[198:201], v151 offset:52224
	ds_read_b128 v[202:205], v151 offset:53248
	ds_read_b128 v[206:209], v151 offset:54272
	ds_read_b128 v[210:213], v151 offset:55296
	ds_read_b128 v[214:217], v151 offset:56320
	global_load_lds_dwordx4 v[144:145], off
	s_add_i32 m0, s42, 0x2000
	s_add_u32 s40, s40, 0x40080
	v_lshl_add_u64 v[144:145], v[218:219], 0, s[14:15]
	s_addc_u32 s41, s41, 0
	s_add_i32 s42, s70, s48
	global_load_lds_dwordx4 v[144:145], off
	v_lshl_add_u64 v[144:145], s[40:41], 0, v[132:133]
	s_mov_b32 m0, s42
	s_nop 0
	global_load_lds_dwordx4 v[144:145], off
	v_lshl_add_u64 v[144:145], s[40:41], 0, v[128:129]
	s_add_i32 m0, s42, 0x2000
	s_nop 0
	global_load_lds_dwordx4 v[144:145], off
	v_lshl_add_u64 v[144:145], v[220:221], 0, s[14:15]
	s_mov_b32 m0, s53
	s_nop 0
	global_load_lds_dwordx4 v[144:145], off
	v_lshl_add_u64 v[144:145], v[222:223], 0, s[14:15]
	s_mov_b32 m0, s54
	s_nop 0
	global_load_lds_dwordx4 v[144:145], off
	s_and_b64 vcc, exec, s[16:17]
	s_cbranch_vccnz .Llatew_1
	s_waitcnt vmcnt(8)
